# v017 + fused epilogue: the 8 row-statistic slot loads issued together (same summation order)
# baseline (speedup 1.0000x reference)
;     __device__ __forceinline__ void fused(f32x4 (&acc)[2][2][4][2], const Unit& u, int wr, int wc, int fr, int fq, PG8_LAS unsigned char* lds, int wid, int lane) const {
;     ...
;         asm volatile("s_waitcnt vmcnt(0) lgkmcnt(0)" ::: "memory"); __builtin_amdgcn_s_barrier(); asm volatile("" ::: "memory");
;         if (wid < 4) {
;             const unsigned* sp = (const unsigned*)slots + (size_t)(u.pm * BM + prow) * 8; float t = 0.f;
; #pragma unroll
;             for (int k = 0; k < 8; ++k) t += __uint_as_float(__hip_atomic_load(sp + k, __ATOMIC_RELAXED, __HIP_MEMORY_SCOPE_AGENT));
;             St[prow] = rsqrtf(t * (1.0f / DM) + EPS);
.LBB0_1117:
	s_waitcnt vmcnt(0) lgkmcnt(0)
	s_barrier
	s_andn2_b64 vcc, exec, s[46:47]
	s_cbranch_vccnz .LBB0_1119
	v_lshlrev_b64 v[162:163], 5, v[162:163]
	v_lshl_add_u64 v[162:163], s[38:39], 0, v[162:163]
	global_load_dword v96, v[162:163], off sc1
	global_load_dword v165, v[162:163], off offset:4 sc1
	global_load_dword v168, v[162:163], off offset:8 sc1
	global_load_dword v169, v[162:163], off offset:12 sc1
	global_load_dword v170, v[162:163], off offset:16 sc1
	global_load_dword v171, v[162:163], off offset:20 sc1
	global_load_dword v172, v[162:163], off offset:24 sc1
	global_load_dword v173, v[162:163], off offset:28 sc1
	s_waitcnt vmcnt(7)
	v_add_f32_e32 v96, 0, v96
	s_waitcnt vmcnt(6)
	v_add_f32_e32 v96, v96, v165
	s_waitcnt vmcnt(5)
	v_add_f32_e32 v96, v96, v168
	s_waitcnt vmcnt(4)
	v_add_f32_e32 v96, v96, v169
	s_waitcnt vmcnt(3)
	v_add_f32_e32 v96, v96, v170
	s_waitcnt vmcnt(2)
	v_add_f32_e32 v96, v96, v171
	s_waitcnt vmcnt(1)
	v_add_f32_e32 v96, v96, v172
	s_waitcnt vmcnt(0)
	v_add_f32_e32 v96, v96, v173
	v_fmamk_f32 v96, v96, 0x3a000000, v198
	v_cmp_gt_f32_e32 vcc, s33, v96
	v_mul_f32_e32 v162, 0x4b800000, v96
	s_nop 0
	v_cndmask_b32_e32 v96, v96, v162, vcc
	v_rsq_f32_e32 v96, v96
	s_nop 0
	v_mul_f32_e32 v162, 0x45800000, v96
	v_cndmask_b32_e32 v96, v96, v162, vcc
	v_lshl_add_u32 v162, v164, 2, 0
	ds_write_b32 v162, v96 offset:8192

;     __device__ __forceinline__ void fused(f32x4 (&acc)[2][2][4][2], const Unit& u, int wr, int wc, int fr, int fq, PG8_LAS unsigned char* lds, int wid, int lane) const {
;     ...
;         asm volatile("s_waitcnt vmcnt(0) lgkmcnt(0)" ::: "memory"); __builtin_amdgcn_s_barrier(); asm volatile("" ::: "memory");
;         if (wid < 4) {
;             const unsigned* sp = (const unsigned*)slots + (size_t)(u.pm * BM + prow) * 8; float t = 0.f;
; #pragma unroll
;             for (int k = 0; k < 8; ++k) t += __uint_as_float(__hip_atomic_load(sp + k, __ATOMIC_RELAXED, __HIP_MEMORY_SCOPE_AGENT));
;             St[prow] = rsqrtf(t * (1.0f / DM) + EPS);
.LBB0_1563:
	s_waitcnt vmcnt(0) lgkmcnt(0)
	s_barrier
	s_andn2_b64 vcc, exec, s[56:57]
	s_cbranch_vccnz .LBB0_1565
	v_lshlrev_b64 v[162:163], 5, v[162:163]
	v_lshl_add_u64 v[162:163], s[50:51], 0, v[162:163]
	global_load_dword v96, v[162:163], off sc1
	global_load_dword v165, v[162:163], off offset:4 sc1
	global_load_dword v168, v[162:163], off offset:8 sc1
	global_load_dword v169, v[162:163], off offset:12 sc1
	global_load_dword v170, v[162:163], off offset:16 sc1
	global_load_dword v171, v[162:163], off offset:20 sc1
	global_load_dword v172, v[162:163], off offset:24 sc1
	global_load_dword v173, v[162:163], off offset:28 sc1
	s_waitcnt vmcnt(7)
	v_add_f32_e32 v96, 0, v96
	s_waitcnt vmcnt(6)
	v_add_f32_e32 v96, v96, v165
	s_waitcnt vmcnt(5)
	v_add_f32_e32 v96, v96, v168
	s_waitcnt vmcnt(4)
	v_add_f32_e32 v96, v96, v169
	s_waitcnt vmcnt(3)
	v_add_f32_e32 v96, v96, v170
	s_waitcnt vmcnt(2)
	v_add_f32_e32 v96, v96, v171
	s_waitcnt vmcnt(1)
	v_add_f32_e32 v96, v96, v172
	s_waitcnt vmcnt(0)
	v_add_f32_e32 v96, v96, v173
	v_fmamk_f32 v96, v96, 0x3a000000, v198
	v_cmp_gt_f32_e32 vcc, s33, v96
	v_mul_f32_e32 v162, 0x4b800000, v96
	s_nop 0
	v_cndmask_b32_e32 v96, v96, v162, vcc
	v_rsq_f32_e32 v96, v96
	s_nop 0
	v_mul_f32_e32 v162, 0x45800000, v96
	v_cndmask_b32_e32 v96, v96, v162, vcc
	v_lshl_add_u32 v162, v164, 2, 0
	ds_write_b32 v162, v96 offset:8192
